# Down GEMM K-loop: segment 1/2 vmcnt waits of the first iteration after a tile epilogue skipped (pre-epilogue DMA already complete; epilogue stores drain under the MFMAs)
# speedup vs baseline: 1.0048x; 1.0003x over previous
; #define PG8_STAGE(bufoff, gbase, voff) do { _Pragma("unroll") for (int _i = 0; _i < 2; ++_i) \
;         __builtin_amdgcn_global_load_lds((const unsigned*)((const char*)(gbase) + (voff)[_i]), (PG8_LAS unsigned*)(lds + (bufoff) + ldsw + _i * 8192), 16, 0, 0); } while (0)
; #define PG8_WAIT_V(n) asm volatile("s_waitcnt vmcnt(" #n ")" ::: "memory")
; #define PG8_BAR __builtin_amdgcn_s_barrier()
; template <class Epi, class Sched, bool ALIGN_EPI = false, bool SP2 = false>
; __device__ __forceinline__ void gemm_phase(PG8_LAS unsigned char* lds, const Gemm g, const Sched& S, const Epi& E) {
;     ...
;     for (int i = 0; i < 2; ++i) { int R, C; stage_rc(tid * 16 + i * 8192, R, C); const int Rb = Epi::PERM ? ((R & ~31) + perm32(R & 31)) : R;
;         voffA[i] = (unsigned)(R * K + C) * 2u; voffB[i] = (unsigned)(Rb * K + C) * 2u; }
;     const size_t kstep = (size_t)(BK * 2);
;     const size_t hstep = (size_t)HALF * K * 2;
;     const size_t tstep = 2 * hstep;
;     const unsigned ldsw = (unsigned)wid * 1024u;
;     const int aoff = lds_byte(wr * 64 + fr, fq * 8), boff = lds_byte(wc * 32 + fr, fq * 8);
;     ...
;     Unit cur, nxt; int ui = 0;
;     if (!S.next(0, cur)) return;
;     f32x4 acc[2][2][4][2];
; #pragma unroll
;     for (int a = 0; a < 2; ++a)
; #pragma unroll
;         for (int b = 0; b < 2; ++b)
; #pragma unroll
;             for (int m = 0; m < 4; ++m)
; #pragma unroll
;                 for (int n = 0; n < 2; ++n) acc[a][b][m][n] = (f32x4){0.f, 0.f, 0.f, 0.f};
;     bf16x8 At[4][2], B0[2][2], B1[2][2];
;     const char* cA = (const char*)g.A + (size_t)cur.pm * tstep; const char* cB = (const char*)g.Bt + (size_t)cur.pn * tstep;
;     S.a_ready(cur);
;     if constexpr (SP2) {
;         PG8_STAGE(PG8_SB(0, 0), cB, voffB); PG8_STAGE(PG8_SB(0, 1), cB + hstep, voffB); PG8_STAGE(PG8_SA(0, 0), cA, voffA); PG8_STAGE(PG8_SA(0, 1), cA + hstep, voffA);
;         if (wr == 1) PG8_BAR;
;         PG8_WAIT_V(2); PG8_BAR;
;         PG8_STAGE(PG8_SB(1, 0), cB + kstep, voffB); PG8_STAGE(PG8_SA(1, 0), cA + kstep, voffA); PG8_STAGE(PG8_SB(1, 1), cB + hstep + kstep, voffB);
;         PG8_WAIT_V(6); PG8_BAR;
.LBB0_250:
	v_readlane_b32 s5, v254, 14
	v_readlane_b32 s76, v253, 10
	s_cmp_eq_u32 s5, 0
	v_readlane_b32 s77, v253, 11
	v_readlane_b32 s78, v253, 12
	v_readlane_b32 s79, v253, 13
	s_cselect_b32 s27, s77, 0
	s_cselect_b32 s26, s76, 0
	s_cselect_b32 s61, s79, 0
	s_cselect_b32 s60, s78, 0
	s_lshl_b32 s0, s0, 5
	s_and_b32 s74, s0, 0x60
	s_add_i32 m0, s41, 0x18000
	v_lshl_add_u64 v[8:9], v[8:9], 0, s[28:29]
	s_lshl_b32 s73, s1, 6
	s_lshl_b32 s5, s1, 13
	s_lshl_b32 s6, s74, 7
	s_waitcnt vmcnt(2)
	s_barrier
	global_load_lds_dwordx4 v[8:9], off
	v_lshl_add_u64 v[6:7], v[6:7], 0, s[28:29]
	s_add_i32 m0, s41, 0x1a000
	s_add_i32 s75, s41, 0x8000
	s_add_i32 s76, s41, 0xa000
	global_load_lds_dwordx4 v[6:7], off
	v_lshl_add_u64 v[2:3], v[2:3], 0, s[28:29]
	s_mov_b32 m0, s75
	s_add_u32 s0, s36, 0xb0080
	global_load_lds_dwordx4 v[2:3], off
	v_lshl_add_u64 v[2:3], v[4:5], 0, s[28:29]
	s_mov_b32 m0, s76
	s_addc_u32 s1, s37, 0
	global_load_lds_dwordx4 v[2:3], off
	s_add_i32 m0, s41, 0x1c000
	v_lshl_add_u64 v[2:3], s[0:1], 0, v[222:223]
	global_load_lds_dwordx4 v[2:3], off
	v_lshl_add_u64 v[2:3], s[0:1], 0, v[226:227]
	s_add_i32 m0, s41, 0x1e000
	s_movk_i32 s0, 0x3c0
	global_load_lds_dwordx4 v[2:3], off
	v_and_b32_e32 v2, 48, v0
	v_lshlrev_b32_e32 v3, 6, v0
	v_lshlrev_b32_e32 v0, 2, v0
	v_and_or_b32 v2, v3, s0, v2
	v_and_b32_e32 v0, 32, v0
	s_cmpk_lt_u32 s4, 0x100
	s_movk_i32 s4, 0xb00
	v_bitop3_b32 v4, v2, s5, v0 bitop3:0xde
	v_bitop3_b32 v210, s6, v2, v0 bitop3:0xf6
	v_lshrrev_b32_e32 v2, 1, v14
	v_mul_lo_u32 v0, v16, s4
	s_mov_b32 s5, 0xb000
	v_mad_u64_u32 v[2:3], s[0:1], v2, s5, v[0:1]
	v_or_b32_e32 v0, v2, v15
	v_add_lshl_u32 v0, v0, v17, 1
	s_mov_b64 s[8:9], 0xb0080
	v_lshl_add_u64 v[228:229], v[0:1], 0, s[8:9]
	v_lshrrev_b32_e32 v2, 1, v10
	v_mul_lo_u32 v0, v12, s4
	v_mad_u64_u32 v[2:3], s[0:1], v2, s5, v[0:1]
	s_waitcnt vmcnt(6)
	v_or_b32_e32 v0, v2, v11
	s_cselect_b64 s[6:7], -1, 0
	s_cmp_lg_u64 s[26:27], 0
	v_add_lshl_u32 v0, v0, v13, 1
	s_mov_b32 s77, 0
	s_cselect_b64 s[22:23], -1, 0
	v_lshl_add_u64 v[230:231], v[0:1], 0, s[8:9]
	v_add_u32_e32 v211, 0, v4
	s_barrier
	s_mov_b32 s98, 0
	s_branch .LBB0_253

; #define PG8_STAGE(bufoff, gbase, voff) do { _Pragma("unroll") for (int _i = 0; _i < 2; ++_i) \
;         __builtin_amdgcn_global_load_lds((const unsigned*)((const char*)(gbase) + (voff)[_i]), (PG8_LAS unsigned*)(lds + (bufoff) + ldsw + _i * 8192), 16, 0, 0); } while (0)
; #define PG8_LDA(dst, b, h) do { _Pragma("unroll") for (int m = 0; m < 4; ++m) _Pragma("unroll") for (int k = 0; k < 2; ++k) dst[m][k] = *(const PG8_LAS bf16x8*)(lds + PG8_SA(b, h) + aoff + m * 2048 + k * 1024); } while (0)
; #define PG8_LDB(dst, b, h) do { _Pragma("unroll") for (int n = 0; n < 2; ++n) _Pragma("unroll") for (int k = 0; k < 2; ++k) dst[n][k] = *(const PG8_LAS bf16x8*)(lds + PG8_SB(b, h) + boff + n * 2048 + k * 1024); } while (0)
; #define PG8_MMA(ai, bj, At, Bt) do { __builtin_amdgcn_s_setprio(1); _Pragma("unroll") for (int m = 0; m < 4; ++m) _Pragma("unroll") for (int n = 0; n < 2; ++n) _Pragma("unroll") for (int k = 0; k < 2; ++k) \
;         acc[ai][bj][m][n] = __builtin_amdgcn_mfma_f32_16x16x32_bf16(Bt[n][k], At[m][k], acc[ai][bj][m][n], 0, 0, 0); __builtin_amdgcn_s_setprio(0); } while (0)
; #define PG8_WAIT_V(n) asm volatile("s_waitcnt vmcnt(" #n ")" ::: "memory")
; #define PG8_WAIT_L(n) asm volatile("s_waitcnt lgkmcnt(" #n ")" ::: "memory")
; #define PG8_BAR __builtin_amdgcn_s_barrier()
; #define PG8_SCHED __builtin_amdgcn_sched_barrier(0)
; template <class Epi, class Sched, bool ALIGN_EPI = false, bool SP2 = false>
; __device__ __forceinline__ void gemm_phase(PG8_LAS unsigned char* lds, const Gemm g, const Sched& S, const Epi& E) {
;     ...
;             PG8_LDB(B0, 0, 0); PG8_LDB(B1, 0, 1); PG8_SCHED; PG8_LDA(At, 0, 0); PG8_STAGE(PG8_SA(1, 1), a1 + hstep, voffA);
;             PG8_WAIT_V(8); PG8_WAIT_L(0); PG8_BAR; PG8_MMA(0, 0, At, B0); PG8_MMA(0, 1, At, B1); PG8_BAR; PG8_SCHED;
;             PG8_LDA(At, 0, 1); PG8_STAGE(PG8_SB(0, 0), b2, voffB); PG8_STAGE(PG8_SB(0, 1), b2 + hstep, voffB); PG8_STAGE(PG8_SA(0, 0), a2, voffA);
;             PG8_WAIT_V(8); PG8_WAIT_L(0); PG8_BAR; PG8_MMA(1, 0, At, B0); PG8_MMA(1, 1, At, B1); PG8_BAR; PG8_SCHED;
.LBB0_264:
	s_add_u32 s4, s52, 0x100
	s_addc_u32 s5, s53, 0
	s_add_i32 s85, 0, 0x10000
	s_cmp_eq_u32 s84, 40
	s_cselect_b32 s39, s9, s5
	s_cselect_b32 s38, s8, s4
	v_add_u32_e32 v0, s85, v210
	s_cselect_b32 s37, s65, s83
	s_cselect_b32 s36, s64, s82
	s_add_i32 s86, 0, 0x14000
	ds_read_b128 v[66:69], v0
	ds_read_b128 v[70:73], v0 offset:1024
	ds_read_b128 v[74:77], v0 offset:2048
	ds_read_b128 v[78:81], v0 offset:3072
	v_add_u32_e32 v0, s86, v210
	ds_read_b128 v[146:149], v0
	ds_read_b128 v[150:153], v0 offset:1024
	ds_read_b128 v[154:157], v0 offset:2048
	ds_read_b128 v[158:161], v0 offset:3072
	v_lshl_add_u64 v[194:195], s[52:53], 0, v[230:231]
	s_add_i32 m0, s41, 0xc000
	ds_read_b128 v[162:165], v211
	ds_read_b128 v[166:169], v211 offset:1024
	ds_read_b128 v[170:173], v211 offset:2048
	ds_read_b128 v[174:177], v211 offset:3072
	ds_read_b128 v[178:181], v211 offset:4096
	ds_read_b128 v[182:185], v211 offset:5120
	ds_read_b128 v[186:189], v211 offset:6144
	ds_read_b128 v[190:193], v211 offset:7168
	global_load_lds_dwordx4 v[194:195], off
	v_lshl_add_u64 v[194:195], s[52:53], 0, v[228:229]
	s_add_i32 m0, s41, 0xe000
	s_nop 0
	global_load_lds_dwordx4 v[194:195], off
	s_cmp_lg_u32 s98, 0
	s_cbranch_scc1 .Lrw_dn_1
	s_waitcnt vmcnt(8)
.Lrw_dn_1:
	s_waitcnt lgkmcnt(0)
	s_barrier
	s_setprio 1
	s_waitcnt lgkmcnt(0)
	v_mfma_f32_16x16x32_bf16 v[142:145], v[66:69], v[162:165], v[142:145]
	v_mfma_f32_16x16x32_bf16 v[138:141], v[74:77], v[162:165], v[138:141]
	v_mfma_f32_16x16x32_bf16 v[126:129], v[66:69], v[170:173], v[126:129]
	v_mfma_f32_16x16x32_bf16 v[122:125], v[74:77], v[170:173], v[122:125]
	v_mfma_f32_16x16x32_bf16 v[110:113], v[66:69], v[178:181], v[110:113]
	v_mfma_f32_16x16x32_bf16 v[106:109], v[74:77], v[178:181], v[106:109]
	v_mfma_f32_16x16x32_bf16 v[94:97], v[66:69], v[186:189], v[94:97]
	v_mfma_f32_16x16x32_bf16 v[90:93], v[74:77], v[186:189], v[90:93]
	v_mfma_f32_16x16x32_bf16 v[142:145], v[70:73], v[166:169], v[142:145]
	v_mfma_f32_16x16x32_bf16 v[138:141], v[78:81], v[166:169], v[138:141]
	v_mfma_f32_16x16x32_bf16 v[126:129], v[70:73], v[174:177], v[126:129]
	v_mfma_f32_16x16x32_bf16 v[122:125], v[78:81], v[174:177], v[122:125]
	v_mfma_f32_16x16x32_bf16 v[110:113], v[70:73], v[182:185], v[110:113]
	v_mfma_f32_16x16x32_bf16 v[106:109], v[78:81], v[182:185], v[106:109]
	v_mfma_f32_16x16x32_bf16 v[94:97], v[70:73], v[190:193], v[94:97]
	v_mfma_f32_16x16x32_bf16 v[90:93], v[78:81], v[190:193], v[90:93]
	s_setprio 0
	s_setprio 1
	v_mfma_f32_16x16x32_bf16 v[134:137], v[146:149], v[162:165], v[134:137]
	v_mfma_f32_16x16x32_bf16 v[130:133], v[154:157], v[162:165], v[130:133]
	v_mfma_f32_16x16x32_bf16 v[118:121], v[146:149], v[170:173], v[118:121]
	v_mfma_f32_16x16x32_bf16 v[114:117], v[154:157], v[170:173], v[114:117]
	v_mfma_f32_16x16x32_bf16 v[102:105], v[146:149], v[178:181], v[102:105]
	v_mfma_f32_16x16x32_bf16 v[98:101], v[154:157], v[178:181], v[98:101]
	v_mfma_f32_16x16x32_bf16 v[86:89], v[146:149], v[186:189], v[86:89]
	v_mfma_f32_16x16x32_bf16 v[82:85], v[154:157], v[186:189], v[82:85]
	v_mfma_f32_16x16x32_bf16 v[134:137], v[150:153], v[166:169], v[134:137]
	v_mfma_f32_16x16x32_bf16 v[130:133], v[158:161], v[166:169], v[130:133]
	v_mfma_f32_16x16x32_bf16 v[118:121], v[150:153], v[174:177], v[118:121]
	v_mfma_f32_16x16x32_bf16 v[114:117], v[158:161], v[174:177], v[114:117]
	v_mfma_f32_16x16x32_bf16 v[102:105], v[150:153], v[182:185], v[102:105]
	v_mfma_f32_16x16x32_bf16 v[98:101], v[158:161], v[182:185], v[98:101]
	v_mfma_f32_16x16x32_bf16 v[86:89], v[150:153], v[190:193], v[86:89]
	v_mfma_f32_16x16x32_bf16 v[82:85], v[158:161], v[190:193], v[82:85]
	s_setprio 0
	s_barrier
	s_add_i32 s52, s85, s40
	v_lshl_add_u64 v[194:195], s[36:37], 0, v[222:223]
	s_mov_b32 m0, s52
	ds_read_b128 v[162:165], v211 offset:16384
	ds_read_b128 v[166:169], v211 offset:17408
	ds_read_b128 v[170:173], v211 offset:18432
	ds_read_b128 v[174:177], v211 offset:19456
	ds_read_b128 v[178:181], v211 offset:20480
	ds_read_b128 v[182:185], v211 offset:21504
	ds_read_b128 v[186:189], v211 offset:22528
	ds_read_b128 v[190:193], v211 offset:23552
	global_load_lds_dwordx4 v[194:195], off
	s_add_i32 m0, s52, 0x2000
	s_add_u32 s52, s36, 0xb0000
	v_lshl_add_u64 v[196:197], s[36:37], 0, v[226:227]
	s_addc_u32 s53, s37, 0
	s_add_i32 s85, s86, s40
	global_load_lds_dwordx4 v[196:197], off
	v_lshl_add_u64 v[198:199], s[52:53], 0, v[222:223]
	s_mov_b32 m0, s85
	v_lshl_add_u64 v[200:201], s[38:39], 0, v[224:225]
	global_load_lds_dwordx4 v[198:199], off
	v_lshl_add_u64 v[198:199], s[52:53], 0, v[226:227]
	s_add_i32 m0, s85, 0x2000
	s_nop 0
	global_load_lds_dwordx4 v[198:199], off
	v_lshl_add_u64 v[198:199], s[38:39], 0, v[220:221]
	s_mov_b32 m0, s41
	s_nop 0
	global_load_lds_dwordx4 v[198:199], off
	s_mov_b32 m0, s70
	s_nop 0
	global_load_lds_dwordx4 v[200:201], off
	s_cmp_lg_u32 s98, 0
	s_cbranch_scc1 .Lrw_dn_2
	s_waitcnt vmcnt(8)
; #define PG8_STAGE(bufoff, gbase, voff) do { _Pragma("unroll") for (int _i = 0; _i < 2; ++_i) \
;         __builtin_amdgcn_global_load_lds((const unsigned*)((const char*)(gbase) + (voff)[_i]), (PG8_LAS unsigned*)(lds + (bufoff) + ldsw + _i * 8192), 16, 0, 0); } while (0)
; #define PG8_LDA(dst, b, h) do { _Pragma("unroll") for (int m = 0; m < 4; ++m) _Pragma("unroll") for (int k = 0; k < 2; ++k) dst[m][k] = *(const PG8_LAS bf16x8*)(lds + PG8_SA(b, h) + aoff + m * 2048 + k * 1024); } while (0)
; #define PG8_LDB(dst, b, h) do { _Pragma("unroll") for (int n = 0; n < 2; ++n) _Pragma("unroll") for (int k = 0; k < 2; ++k) dst[n][k] = *(const PG8_LAS bf16x8*)(lds + PG8_SB(b, h) + boff + n * 2048 + k * 1024); } while (0)
; #define PG8_MMA(ai, bj, At, Bt) do { __builtin_amdgcn_s_setprio(1); _Pragma("unroll") for (int m = 0; m < 4; ++m) _Pragma("unroll") for (int n = 0; n < 2; ++n) _Pragma("unroll") for (int k = 0; k < 2; ++k) \
;         acc[ai][bj][m][n] = __builtin_amdgcn_mfma_f32_16x16x32_bf16(Bt[n][k], At[m][k], acc[ai][bj][m][n], 0, 0, 0); __builtin_amdgcn_s_setprio(0); } while (0)
; #define PG8_WAIT_V(n) asm volatile("s_waitcnt vmcnt(" #n ")" ::: "memory")
; #define PG8_WAIT_L(n) asm volatile("s_waitcnt lgkmcnt(" #n ")" ::: "memory")
; #define PG8_BAR __builtin_amdgcn_s_barrier()
; #define PG8_SCHED __builtin_amdgcn_sched_barrier(0)
; template <class Epi, class Sched, bool ALIGN_EPI = false, bool SP2 = false>
; __device__ __forceinline__ void gemm_phase(PG8_LAS unsigned char* lds, const Gemm g, const Sched& S, const Epi& E) {
;     ...
;             PG8_WAIT_V(8); PG8_WAIT_L(0); PG8_BAR; PG8_MMA(1, 0, At, B0); PG8_MMA(1, 1, At, B1); PG8_BAR; PG8_SCHED;
;             PG8_LDB(B0, 1, 0); PG8_LDB(B1, 1, 1); PG8_SCHED; PG8_LDA(At, 1, 0); PG8_STAGE(PG8_SA(0, 1), a2 + hstep, voffA);
;             PG8_WAIT_V(8); PG8_WAIT_L(0); PG8_BAR; PG8_MMA(0, 0, At, B0); PG8_MMA(0, 1, At, B1); PG8_BAR; PG8_SCHED;
.Lrw_dn_2:
	s_mov_b32 s98, 0
	s_waitcnt lgkmcnt(0)
	s_barrier
	s_setprio 1
	s_waitcnt lgkmcnt(0)
	v_mfma_f32_16x16x32_bf16 v[62:65], v[66:69], v[162:165], v[62:65]
	v_mfma_f32_16x16x32_bf16 v[58:61], v[74:77], v[162:165], v[58:61]
	v_mfma_f32_16x16x32_bf16 v[46:49], v[66:69], v[170:173], v[46:49]
	v_mfma_f32_16x16x32_bf16 v[42:45], v[74:77], v[170:173], v[42:45]
	v_mfma_f32_16x16x32_bf16 v[30:33], v[66:69], v[178:181], v[30:33]
	v_mfma_f32_16x16x32_bf16 v[26:29], v[74:77], v[178:181], v[26:29]
	v_mfma_f32_16x16x32_bf16 v[14:17], v[66:69], v[186:189], v[14:17]
	v_mfma_f32_16x16x32_bf16 v[10:13], v[74:77], v[186:189], v[10:13]
	v_mfma_f32_16x16x32_bf16 v[62:65], v[70:73], v[166:169], v[62:65]
	v_mfma_f32_16x16x32_bf16 v[58:61], v[78:81], v[166:169], v[58:61]
	v_mfma_f32_16x16x32_bf16 v[46:49], v[70:73], v[174:177], v[46:49]
	v_mfma_f32_16x16x32_bf16 v[42:45], v[78:81], v[174:177], v[42:45]
	v_mfma_f32_16x16x32_bf16 v[30:33], v[70:73], v[182:185], v[30:33]
	v_mfma_f32_16x16x32_bf16 v[26:29], v[78:81], v[182:185], v[26:29]
	v_mfma_f32_16x16x32_bf16 v[14:17], v[70:73], v[190:193], v[14:17]
	v_mfma_f32_16x16x32_bf16 v[10:13], v[78:81], v[190:193], v[10:13]
	s_setprio 0
	s_setprio 1
	v_mfma_f32_16x16x32_bf16 v[54:57], v[146:149], v[162:165], v[54:57]
	v_mfma_f32_16x16x32_bf16 v[50:53], v[154:157], v[162:165], v[50:53]
	v_mfma_f32_16x16x32_bf16 v[38:41], v[146:149], v[170:173], v[38:41]
	v_mfma_f32_16x16x32_bf16 v[34:37], v[154:157], v[170:173], v[34:37]
	v_mfma_f32_16x16x32_bf16 v[22:25], v[146:149], v[178:181], v[22:25]
	v_mfma_f32_16x16x32_bf16 v[18:21], v[154:157], v[178:181], v[18:21]
	v_mfma_f32_16x16x32_bf16 v[6:9], v[146:149], v[186:189], v[6:9]
	v_mfma_f32_16x16x32_bf16 v[2:5], v[154:157], v[186:189], v[2:5]
	v_mfma_f32_16x16x32_bf16 v[54:57], v[150:153], v[166:169], v[54:57]
	v_mfma_f32_16x16x32_bf16 v[50:53], v[158:161], v[166:169], v[50:53]
	v_mfma_f32_16x16x32_bf16 v[38:41], v[150:153], v[174:177], v[38:41]
	v_mfma_f32_16x16x32_bf16 v[34:37], v[158:161], v[174:177], v[34:37]
	v_mfma_f32_16x16x32_bf16 v[22:25], v[150:153], v[182:185], v[22:25]
	v_mfma_f32_16x16x32_bf16 v[18:21], v[158:161], v[182:185], v[18:21]
	v_mfma_f32_16x16x32_bf16 v[6:9], v[150:153], v[190:193], v[6:9]
	v_mfma_f32_16x16x32_bf16 v[2:5], v[158:161], v[190:193], v[2:5]
	s_setprio 0
	s_barrier
	s_add_i32 s52, 0, 0x18000
	v_add_u32_e32 v0, s52, v210
	s_add_i32 s53, 0, 0x1c000
	ds_read_b128 v[66:69], v0
	ds_read_b128 v[70:73], v0 offset:1024
	ds_read_b128 v[74:77], v0 offset:2048
	ds_read_b128 v[78:81], v0 offset:3072
	v_add_u32_e32 v0, s53, v210
	ds_read_b128 v[146:149], v0
	ds_read_b128 v[150:153], v0 offset:1024
	ds_read_b128 v[154:157], v0 offset:2048
	ds_read_b128 v[158:161], v0 offset:3072
	s_add_u32 s38, s38, 0xb0000
	s_addc_u32 s39, s39, 0
	s_mov_b32 m0, s71
	v_lshl_add_u64 v[202:203], s[38:39], 0, v[220:221]
	ds_read_b128 v[162:165], v211 offset:32768
	ds_read_b128 v[166:169], v211 offset:33792
	ds_read_b128 v[170:173], v211 offset:34816
	ds_read_b128 v[174:177], v211 offset:35840
	ds_read_b128 v[178:181], v211 offset:36864
	ds_read_b128 v[182:185], v211 offset:37888
	ds_read_b128 v[186:189], v211 offset:38912
	ds_read_b128 v[190:193], v211 offset:39936
	global_load_lds_dwordx4 v[202:203], off
	v_lshl_add_u64 v[202:203], s[38:39], 0, v[224:225]
	s_mov_b32 m0, s72
	s_nop 0
	global_load_lds_dwordx4 v[202:203], off
	s_waitcnt vmcnt(8)
	s_waitcnt lgkmcnt(0)
	s_barrier
	s_setprio 1
	s_waitcnt lgkmcnt(0)
	v_mfma_f32_16x16x32_bf16 v[142:145], v[66:69], v[162:165], v[142:145]
	v_mfma_f32_16x16x32_bf16 v[138:141], v[74:77], v[162:165], v[138:141]
	v_mfma_f32_16x16x32_bf16 v[126:129], v[66:69], v[170:173], v[126:129]
	v_mfma_f32_16x16x32_bf16 v[122:125], v[74:77], v[170:173], v[122:125]
	v_mfma_f32_16x16x32_bf16 v[110:113], v[66:69], v[178:181], v[110:113]
	v_mfma_f32_16x16x32_bf16 v[106:109], v[74:77], v[178:181], v[106:109]
	v_mfma_f32_16x16x32_bf16 v[94:97], v[66:69], v[186:189], v[94:97]
	v_mfma_f32_16x16x32_bf16 v[90:93], v[74:77], v[186:189], v[90:93]
	v_mfma_f32_16x16x32_bf16 v[142:145], v[70:73], v[166:169], v[142:145]
	v_mfma_f32_16x16x32_bf16 v[138:141], v[78:81], v[166:169], v[138:141]
	v_mfma_f32_16x16x32_bf16 v[126:129], v[70:73], v[174:177], v[126:129]
	v_mfma_f32_16x16x32_bf16 v[122:125], v[78:81], v[174:177], v[122:125]
	v_mfma_f32_16x16x32_bf16 v[110:113], v[70:73], v[182:185], v[110:113]
	v_mfma_f32_16x16x32_bf16 v[106:109], v[78:81], v[182:185], v[106:109]
	v_mfma_f32_16x16x32_bf16 v[94:97], v[70:73], v[190:193], v[94:97]
	v_mfma_f32_16x16x32_bf16 v[90:93], v[78:81], v[190:193], v[90:93]
	s_setprio 0
	s_setprio 1
	v_mfma_f32_16x16x32_bf16 v[134:137], v[146:149], v[162:165], v[134:137]
	v_mfma_f32_16x16x32_bf16 v[130:133], v[154:157], v[162:165], v[130:133]
	v_mfma_f32_16x16x32_bf16 v[118:121], v[146:149], v[170:173], v[118:121]
	v_mfma_f32_16x16x32_bf16 v[114:117], v[154:157], v[170:173], v[114:117]
	v_mfma_f32_16x16x32_bf16 v[102:105], v[146:149], v[178:181], v[102:105]
	v_mfma_f32_16x16x32_bf16 v[98:101], v[154:157], v[178:181], v[98:101]
	v_mfma_f32_16x16x32_bf16 v[86:89], v[146:149], v[186:189], v[86:89]
	v_mfma_f32_16x16x32_bf16 v[82:85], v[154:157], v[186:189], v[82:85]
	v_mfma_f32_16x16x32_bf16 v[134:137], v[150:153], v[166:169], v[134:137]
	v_mfma_f32_16x16x32_bf16 v[130:133], v[158:161], v[166:169], v[130:133]
	v_mfma_f32_16x16x32_bf16 v[118:121], v[150:153], v[174:177], v[118:121]
	v_mfma_f32_16x16x32_bf16 v[114:117], v[158:161], v[174:177], v[114:117]
	v_mfma_f32_16x16x32_bf16 v[102:105], v[150:153], v[182:185], v[102:105]
	v_mfma_f32_16x16x32_bf16 v[98:101], v[158:161], v[182:185], v[98:101]
	v_mfma_f32_16x16x32_bf16 v[86:89], v[150:153], v[190:193], v[86:89]
	v_mfma_f32_16x16x32_bf16 v[82:85], v[158:161], v[190:193], v[82:85]
	s_setprio 0
	s_barrier
; #define PG8_STAGE(bufoff, gbase, voff) do { _Pragma("unroll") for (int _i = 0; _i < 2; ++_i) \
;         __builtin_amdgcn_global_load_lds((const unsigned*)((const char*)(gbase) + (voff)[_i]), (PG8_LAS unsigned*)(lds + (bufoff) + ldsw + _i * 8192), 16, 0, 0); } while (0)
; #define PG8_LDA(dst, b, h) do { _Pragma("unroll") for (int m = 0; m < 4; ++m) _Pragma("unroll") for (int k = 0; k < 2; ++k) dst[m][k] = *(const PG8_LAS bf16x8*)(lds + PG8_SA(b, h) + aoff + m * 2048 + k * 1024); } while (0)
; #define PG8_MMA(ai, bj, At, Bt) do { __builtin_amdgcn_s_setprio(1); _Pragma("unroll") for (int m = 0; m < 4; ++m) _Pragma("unroll") for (int n = 0; n < 2; ++n) _Pragma("unroll") for (int k = 0; k < 2; ++k) \
;         acc[ai][bj][m][n] = __builtin_amdgcn_mfma_f32_16x16x32_bf16(Bt[n][k], At[m][k], acc[ai][bj][m][n], 0, 0, 0); __builtin_amdgcn_s_setprio(0); } while (0)
; #define PG8_WAIT_V(n) asm volatile("s_waitcnt vmcnt(" #n ")" ::: "memory")
; #define PG8_WAIT_L(n) asm volatile("s_waitcnt lgkmcnt(" #n ")" ::: "memory")
; #define PG8_BAR __builtin_amdgcn_s_barrier()
; #define PG8_SCHED __builtin_amdgcn_sched_barrier(0)
; template <class Epi, class Sched, bool ALIGN_EPI = false, bool SP2 = false>
; __device__ __forceinline__ void gemm_phase(PG8_LAS unsigned char* lds, const Gemm g, const Sched& S, const Epi& E) {
;     ...
;         for (int t = 0; t < nt; t += 2) {
;     ...
;             PG8_LDA(At, 1, 1); PG8_STAGE(PG8_SB(1, 0), b3, voffB); PG8_STAGE(PG8_SB(1, 1), b3 + hstep, voffB); PG8_STAGE(PG8_SA(1, 0), a3, voffA);
;             PG8_WAIT_V(8); PG8_WAIT_L(0); PG8_BAR; PG8_MMA(1, 0, At, B0); PG8_MMA(1, 1, At, B1); PG8_BAR; PG8_SCHED;
	s_add_i32 s38, s52, s40
	v_lshl_add_u64 v[194:195], v[194:195], 0, s[28:29]
	s_mov_b32 m0, s38
	ds_read_b128 v[162:165], v211 offset:49152
	ds_read_b128 v[166:169], v211 offset:50176
	ds_read_b128 v[170:173], v211 offset:51200
	ds_read_b128 v[174:177], v211 offset:52224
	ds_read_b128 v[178:181], v211 offset:53248
	ds_read_b128 v[182:185], v211 offset:54272
	ds_read_b128 v[186:189], v211 offset:55296
	ds_read_b128 v[190:193], v211 offset:56320
	global_load_lds_dwordx4 v[194:195], off
	s_add_i32 m0, s38, 0x2000
	s_add_u32 s36, s36, 0xb0080
	v_lshl_add_u64 v[194:195], v[196:197], 0, s[28:29]
	s_addc_u32 s37, s37, 0
	s_add_i32 s38, s53, s40
	global_load_lds_dwordx4 v[194:195], off
	v_lshl_add_u64 v[194:195], s[36:37], 0, v[222:223]
	s_mov_b32 m0, s38
	s_nop 0
	global_load_lds_dwordx4 v[194:195], off
	v_lshl_add_u64 v[194:195], s[36:37], 0, v[226:227]
	s_add_i32 m0, s38, 0x2000
	s_nop 0
	global_load_lds_dwordx4 v[194:195], off
	v_lshl_add_u64 v[194:195], v[198:199], 0, s[28:29]
	s_mov_b32 m0, s75
	s_nop 0
	global_load_lds_dwordx4 v[194:195], off
	v_lshl_add_u64 v[194:195], v[200:201], 0, s[28:29]
	s_mov_b32 m0, s76
	s_nop 0
	global_load_lds_dwordx4 v[194:195], off
	s_waitcnt vmcnt(8)
	s_waitcnt lgkmcnt(0)
	s_barrier
	s_setprio 1
	s_waitcnt lgkmcnt(0)
	v_mfma_f32_16x16x32_bf16 v[62:65], v[66:69], v[162:165], v[62:65]
	v_mfma_f32_16x16x32_bf16 v[58:61], v[74:77], v[162:165], v[58:61]
	v_mfma_f32_16x16x32_bf16 v[46:49], v[66:69], v[170:173], v[46:49]
	v_mfma_f32_16x16x32_bf16 v[42:45], v[74:77], v[170:173], v[42:45]
	v_mfma_f32_16x16x32_bf16 v[30:33], v[66:69], v[178:181], v[30:33]
	v_mfma_f32_16x16x32_bf16 v[26:29], v[74:77], v[178:181], v[26:29]
	v_mfma_f32_16x16x32_bf16 v[14:17], v[66:69], v[186:189], v[14:17]
	v_mfma_f32_16x16x32_bf16 v[10:13], v[74:77], v[186:189], v[10:13]
	v_mfma_f32_16x16x32_bf16 v[62:65], v[70:73], v[166:169], v[62:65]
	v_mfma_f32_16x16x32_bf16 v[58:61], v[78:81], v[166:169], v[58:61]
	v_mfma_f32_16x16x32_bf16 v[46:49], v[70:73], v[174:177], v[46:49]
	v_mfma_f32_16x16x32_bf16 v[42:45], v[78:81], v[174:177], v[42:45]
	v_mfma_f32_16x16x32_bf16 v[30:33], v[70:73], v[182:185], v[30:33]
	v_mfma_f32_16x16x32_bf16 v[26:29], v[78:81], v[182:185], v[26:29]
	v_mfma_f32_16x16x32_bf16 v[14:17], v[70:73], v[190:193], v[14:17]
	v_mfma_f32_16x16x32_bf16 v[10:13], v[78:81], v[190:193], v[10:13]
	s_setprio 0
	s_setprio 1
	v_mfma_f32_16x16x32_bf16 v[54:57], v[146:149], v[162:165], v[54:57]
	v_mfma_f32_16x16x32_bf16 v[50:53], v[154:157], v[162:165], v[50:53]
	v_mfma_f32_16x16x32_bf16 v[38:41], v[146:149], v[170:173], v[38:41]
	v_mfma_f32_16x16x32_bf16 v[34:37], v[154:157], v[170:173], v[34:37]
	v_mfma_f32_16x16x32_bf16 v[22:25], v[146:149], v[178:181], v[22:25]
	v_mfma_f32_16x16x32_bf16 v[18:21], v[154:157], v[178:181], v[18:21]
	v_mfma_f32_16x16x32_bf16 v[6:9], v[146:149], v[186:189], v[6:9]
	v_mfma_f32_16x16x32_bf16 v[2:5], v[154:157], v[186:189], v[2:5]
	v_mfma_f32_16x16x32_bf16 v[54:57], v[150:153], v[166:169], v[54:57]
	v_mfma_f32_16x16x32_bf16 v[50:53], v[158:161], v[166:169], v[50:53]
	v_mfma_f32_16x16x32_bf16 v[38:41], v[150:153], v[174:177], v[38:41]
	v_mfma_f32_16x16x32_bf16 v[34:37], v[158:161], v[174:177], v[34:37]
	v_mfma_f32_16x16x32_bf16 v[22:25], v[150:153], v[182:185], v[22:25]
	v_mfma_f32_16x16x32_bf16 v[18:21], v[158:161], v[182:185], v[18:21]
	v_mfma_f32_16x16x32_bf16 v[6:9], v[150:153], v[190:193], v[6:9]
	v_mfma_f32_16x16x32_bf16 v[2:5], v[158:161], v[190:193], v[2:5]
	s_setprio 0
	s_barrier
	s_add_i32 s84, s84, 2
	s_add_u32 s82, s82, 0x100
	s_addc_u32 s83, s83, 0
	s_cmp_gt_u32 s84, 41
	s_mov_b64 s[52:53], s[4:5]
	s_cbranch_scc0 .LBB0_264
	s_and_b64 vcc, exec, s[6:7]
	s_cbranch_vccz .LBB0_267
	s_barrier

; #define PG8_BAR __builtin_amdgcn_s_barrier()
; template <class Epi, class Sched, bool ALIGN_EPI = false, bool SP2 = false>
; __device__ __forceinline__ void gemm_phase(PG8_LAS unsigned char* lds, const Gemm g, const Sched& S, const Epi& E) {
;     ...
;         if constexpr (!Epi::AFTER_DRAIN) { E(acc, cur, wr, wc, fr, fq); S.done(cur); }
;         if (!has_next) break;
; #pragma unroll
;         for (int a = 0; a < 2; ++a)
; #pragma unroll
;             for (int b = 0; b < 2; ++b)
; #pragma unroll
;                 for (int m = 0; m < 4; ++m)
; #pragma unroll
;                     for (int n = 0; n < 2; ++n) acc[a][b][m][n] = (f32x4){0.f, 0.f, 0.f, 0.f};
;         cur = nxt; cA = nA; cB = nB; ++ui;
;         if constexpr (ALIGN_EPI) { if (wr == 1) PG8_BAR; }
;     }
.LBB0_363:
	s_or_b64 exec, exec, s[4:5]
	s_mov_b32 s98, 1
	s_and_b64 vcc, exec, s[0:1]
	s_mov_b64 s[0:1], -1
	s_cbranch_vccnz .LBB0_252
	s_andn2_b64 vcc, exec, s[24:25]
	s_cbranch_vccnz .LBB0_251
	s_barrier
	s_branch .LBB0_251
